# XCD-local seams with 4us/XCD start stagger (XCD_SLEEP=128); P4/P6' epilogue rewrites (wide d_out stores)
# speedup vs baseline: 1.0127x; 1.0127x over previous
.Lxl_stag_loop:
	s_sleep 127
	s_sleep 1
	s_add_i32 s101, s101, -1
	s_cmp_lg_u32 s101, 0
	s_cbranch_scc1 .Lxl_stag_loop
